# plus O1 wide-tile phase staggered: the second co-resident workgroup (LDS base != 0) starts ~12us later so its K loops overlap the partner's epilogues
# speedup vs baseline: 1.0199x; 1.0074x over previous
;   DI u16* Wt_in_o() const { return (u16*)(ws + WS_Wt_in_o); }
;   DI u16* y0b() const { return (u16*)(ws + WS_y0b); }
; __global__ void __launch_bounds__(256, 2) fwd_megakernel(Params p) {
;     ...
;   for (TileSched ts = tile_sched(128 * 16); ts.t < ts.hi; ts.t += ts.step) {
;     const int mt = ts.t >> 4, n2 = ts.t & 15;
;     gemm_tile_wide<1024>(p.y0b(), 1024, p.Wt_in_o(), 1024, mt * 128, n2 * 256, smem, [&](int half) { epi_o1(p, mt, 2 * n2 + half, (const float*)smem); });
;   }
.LBB0_923:
	s_getreg_b32 s99, hwreg(HW_REG_LDS_ALLOC, 0, 12)
	s_cmp_eq_u32 s99, 0
	s_cbranch_scc1 .Lstag_o1
	s_sleep 127
	s_sleep 127
	s_sleep 127
